# HGRN state update: chunk decays read once per lane pair (one ds_read_b64) and broadcast in the 16-lane row by DPP row_newbcast instead of eight ds_read_b128; QE/KE row addresses from one base register
# speedup vs baseline: 1.0074x; 1.0023x over previous
.LBB0_928:
	s_or_b64 exec, exec, s[0:1]
	v_mov_b32_e32 v2, s35
	s_waitcnt lgkmcnt(0)
	s_barrier
	ds_read_b32 v2, v2
	s_waitcnt lgkmcnt(0)
	v_readfirstlane_b32 s3, v2
	s_cmp_ge_i32 s3, s5
	s_cbranch_scc1 .LBB0_1012
	s_add_u32 s16, s14, 0x2c600000
	s_addc_u32 s17, s15, 0
	s_add_u32 s36, s14, 0x32600000
	s_addc_u32 s37, s15, 0
	v_ashrrev_i32_e32 v6, 4, v0
	s_add_u32 s0, s14, 0x36e00000
	v_writelane_b32 v255, s18, 24
	s_addc_u32 s1, s15, 0
	s_waitcnt vmcnt(0)
	v_lshlrev_b32_e32 v54, 2, v6
	v_writelane_b32 v255, s19, 25
	s_add_u32 s18, s14, 0x4ee00000
	v_ashrrev_i32_e32 v55, 31, v54
	s_addc_u32 s19, s15, 0
	v_lshlrev_b64 v[70:71], 9, v[54:55]
	s_mov_b64 s[14:15], 0x4000
	v_lshl_add_u64 v[86:87], v[70:71], 0, s[14:15]
	s_mov_b64 s[14:15], 0x4200
	v_lshl_add_u64 v[88:89], v[70:71], 0, s[14:15]
	s_mov_b64 s[14:15], 0x4400
	v_lshl_add_u64 v[90:91], v[70:71], 0, s[14:15]
	s_mov_b64 s[14:15], 0x4600
	v_lshl_add_u64 v[92:93], v[70:71], 0, s[14:15]
	s_mov_b64 s[14:15], 0x6000
	v_lshl_add_u64 v[94:95], v[70:71], 0, s[14:15]
	s_mov_b64 s[14:15], 0x6200
	v_lshl_add_u64 v[96:97], v[70:71], 0, s[14:15]
	s_mov_b64 s[14:15], 0x6400
	v_lshl_add_u64 v[98:99], v[70:71], 0, s[14:15]
	s_mov_b64 s[14:15], 0x6600
	v_lshl_add_u64 v[100:101], v[70:71], 0, s[14:15]
	s_mov_b64 s[14:15], 0x8000
	v_lshl_add_u64 v[102:103], v[70:71], 0, s[14:15]
	s_mov_b64 s[14:15], 0x8200
	v_lshl_add_u64 v[104:105], v[70:71], 0, s[14:15]
	s_mov_b64 s[14:15], 0x8400
	v_lshl_add_u64 v[106:107], v[70:71], 0, s[14:15]
	s_mov_b64 s[14:15], 0x8600
	v_lshl_add_u64 v[108:109], v[70:71], 0, s[14:15]
	s_mov_b64 s[14:15], 0xa000
	v_lshl_add_u64 v[110:111], v[70:71], 0, s[14:15]
	s_mov_b64 s[14:15], 0xa200
	v_lshl_add_u64 v[112:113], v[70:71], 0, s[14:15]
	s_mov_b64 s[14:15], 0xa400
	v_lshl_add_u64 v[114:115], v[70:71], 0, s[14:15]
	s_mov_b64 s[14:15], 0xa600
	v_lshl_add_u64 v[116:117], v[70:71], 0, s[14:15]
	s_mov_b64 s[14:15], 0xc000
	v_lshl_add_u64 v[118:119], v[70:71], 0, s[14:15]
	s_mov_b64 s[14:15], 0xc200
	v_lshl_add_u64 v[120:121], v[70:71], 0, s[14:15]
	s_mov_b64 s[14:15], 0xc400
	v_lshl_add_u64 v[122:123], v[70:71], 0, s[14:15]
	s_mov_b64 s[14:15], 0xc600
	v_lshl_add_u64 v[124:125], v[70:71], 0, s[14:15]
	s_mov_b64 s[14:15], 0xe000
	v_lshl_add_u64 v[126:127], v[70:71], 0, s[14:15]
	s_mov_b64 s[14:15], 0xe200
	s_lshl_b32 s20, s2, 4
	v_lshl_add_u64 v[128:129], v[70:71], 0, s[14:15]
	s_mov_b64 s[14:15], 0xe400
	s_ashr_i32 s21, s20, 31
	v_lshl_add_u64 v[130:131], v[70:71], 0, s[14:15]
	s_mov_b64 s[14:15], 0xe600
	v_or_b32_e32 v56, 1, v54
	v_lshl_add_u64 v[132:133], v[70:71], 0, s[14:15]
	v_lshlrev_b32_e32 v2, 2, v0
	s_lshl_b64 s[14:15], s[20:21], 2
	v_and_b32_e32 v50, 15, v0
	v_or_b32_e32 v58, 2, v54
	v_ashrrev_i32_e32 v57, 31, v56
	v_and_b32_e32 v51, 15, v0
	v_subrev_u32_e32 v1, 64, v2
	v_cmp_lt_i32_e32 vcc, 15, v0
	s_add_u32 s12, s12, s14
	v_lshlrev_b64 v[72:73], 9, v[56:57]
	v_ashrrev_i32_e32 v59, 31, v58
	v_cndmask_b32_e32 v57, v2, v1, vcc
	v_add_u32_e32 v1, 0xffffff80, v2
	v_cmp_lt_i32_e32 vcc, 31, v0
	v_lshlrev_b32_e32 v4, 2, v50
	s_addc_u32 s13, s13, s15
	v_mov_b32_e32 v5, v3
	v_or_b32_e32 v52, s20, v50
	v_lshlrev_b64 v[74:75], 9, v[58:59]
	v_not_b32_e32 v53, v51
	v_cndmask_b32_e32 v59, v2, v1, vcc
	v_cmp_gt_u32_e64 s[44:45], 16, v0
	v_and_b32_e32 v155, -16, v0
	v_lshl_add_u64 v[0:1], s[12:13], 0, v[4:5]
	s_mov_b64 s[12:13], 0x6480000
	s_movk_i32 s2, 0x220
	v_lshl_add_u64 v[138:139], v[0:1], 0, s[12:13]
	v_mad_u64_u32 v[140:141], s[12:13], v6, s2, v[52:53]
	s_movk_i32 s2, 0x88
	v_mad_u64_u32 v[142:143], s[12:13], v56, s2, v[52:53]
	v_add_u32_e32 v62, 16, v54
	s_waitcnt vmcnt(1)
	v_add_u32_e32 v66, 18, v54
	v_readlane_b32 s12, v254, 19
	v_or_b32_e32 v60, 3, v54
	v_add_u32_e32 v64, 17, v54
	v_add_u32_e32 v68, 19, v54
	v_ashrrev_i32_e32 v63, 31, v62
	v_ashrrev_i32_e32 v67, 31, v66
	v_add_u32_e32 v134, s20, v54
	v_readlane_b32 s13, v254, 20
	s_add_u32 s12, s12, s14
	v_ashrrev_i32_e32 v61, 31, v60
	v_lshlrev_b64 v[78:79], 9, v[62:63]
	v_ashrrev_i32_e32 v65, 31, v64
	v_lshlrev_b64 v[82:83], 9, v[66:67]
	v_ashrrev_i32_e32 v69, 31, v68
	v_mul_lo_u32 v63, v52, 48
	v_mad_u32_u24 v67, v134, 24, v51
	v_lshlrev_b32_e32 v2, 1, v134
	v_lshlrev_b32_e32 v154, 3, v6
	v_xor_b32_e32 v158, -2, v54
	v_xor_b32_e32 v160, -3, v54
	v_xor_b32_e32 v162, -4, v54
	v_add_u32_e32 v171, 0x88, v142
	v_add_u32_e32 v173, 0x110, v142
	v_sub_u32_e32 v0, v50, v54
	s_addc_u32 s13, s13, s15
	v_lshlrev_b64 v[76:77], 9, v[60:61]
	v_lshlrev_b64 v[80:81], 9, v[64:65]
	v_lshlrev_b64 v[84:85], 9, v[68:69]
	v_add_u32_e32 v55, 16, v51
	v_cmp_lt_i32_e64 s[40:41], 0, v6
	v_cmp_lt_i32_e64 s[42:43], 1, v6
	v_or_b32_e32 v61, 0xc0, v4
	v_lshl_add_u32 v65, v52, 2, 0
	v_lshl_add_u32 v69, v67, 1, 0
	v_lshl_add_u64 v[136:137], s[0:1], 0, v[2:3]
	v_mul_u32_u24_e32 v135, 0x88, v50
	v_cmp_gt_i32_e64 s[46:47], 2, v6
	v_mul_u32_u24_e32 v156, 48, v50
	v_sub_u32_e32 v157, 0xff, v54
	v_add_u32_e32 v159, 0x100, v158
	v_add_u32_e32 v161, 0x100, v160
	v_add_u32_e32 v163, 0x100, v162
	v_sub_u32_e32 v164, 0xff, v51
	v_sub_u32_e32 v165, 0xef, v54
	v_sub_u32_e32 v166, 0xee, v54
	v_sub_u32_e32 v167, 0xed, v54
	v_sub_u32_e32 v168, 0xec, v54
	v_sub_u32_e32 v169, 0xef, v51
	v_lshl_add_u32 v141, v140, 1, 0
	v_add3_u32 v170, 0, v63, v154
	v_lshl_add_u32 v143, v142, 1, 0
	v_lshl_add_u32 v172, v171, 1, 0
	v_lshl_add_u32 v174, v173, 1, 0
	v_and_b32_e32 v142, 14, v50
	v_lshlrev_b32_e32 v142, 5, v142
	v_and_b32_e32 v171, 1, v50
	v_lshl_add_u32 v142, v171, 3, v142
	v_lshl_add_u32 v142, v54, 2, v142
	v_cmp_gt_i32_e64 s[48:49], 0, v0
	v_cmp_gt_i32_e64 s[50:51], 1, v0
	v_cmp_gt_i32_e64 s[52:53], 2, v0
	v_cmp_gt_i32_e64 s[54:55], 3, v0
	v_not_b32_e32 v175, v54
	v_lshl_add_u64 v[144:145], s[12:13], 0, v[4:5]
	v_sub_u32_e32 v176, 0, v154
	v_add_u32_e32 v177, 32, v51
	v_sub_u32_e32 v178, 0xdf, v51
	v_sub_u32_e32 v179, 0xdf, v54
	v_sub_u32_e32 v180, 0xffffffdf, v51
	v_sub_u32_e32 v181, 0xffffffdf, v54
	s_branch .LBB0_933

.LBB0_947:
	v_lshlrev_b32_e32 v0, 16, v45
	v_mul_f32_e32 v0, 0xbfb8aa3b, v0
	v_exp_f32_e32 v0, v0
	v_lshlrev_b32_e32 v1, 16, v44
	s_sub_i32 s80, 0, s62
	v_lshlrev_b32_e32 v42, 16, v42
	v_min_f32_e32 v0, 0x7149f2ca, v0
	v_add_f32_e32 v2, 1.0, v0
	v_rcp_f32_e32 v44, v2
	v_fma_f32 v0, v183, v0, 1.0
	v_rcp_f32_e32 v184, v0
	v_lshlrev_b32_e32 v40, 16, v40
	v_mul_f32_e32 v45, v0, v44
	v_fma_f32 v44, -v0, v44, 1.0
	v_lshlrev_b32_e32 v0, 16, v43
	v_mul_f32_e32 v0, 0xbfb8aa3b, v0
	v_exp_f32_e32 v0, v0
	v_cndmask_b32_e64 v184, v184, 1.0, s[58:59]
	v_mul_f32_e32 v2, v2, v184
	v_lshlrev_b32_e32 v38, 16, v38
	v_min_f32_e32 v0, 0x7149f2ca, v0
	v_add_f32_e32 v43, 1.0, v0
	v_rcp_f32_e32 v184, v43
	v_fma_f32 v0, v183, v0, 1.0
	v_rcp_f32_e32 v186, v0
	v_mul_f32_e32 v185, v0, v184
	v_fma_f32 v184, -v0, v184, 1.0
	v_lshlrev_b32_e32 v0, 16, v41
	v_mul_f32_e32 v0, 0xbfb8aa3b, v0
	v_exp_f32_e32 v0, v0
	v_cndmask_b32_e64 v186, v186, 1.0, s[58:59]
	v_mul_f32_e32 v43, v43, v186
	v_mul_f32_e32 v185, v45, v185
	v_min_f32_e32 v0, 0x7149f2ca, v0
	v_add_f32_e32 v41, 1.0, v0
	v_rcp_f32_e32 v186, v41
	v_fma_f32 v0, v183, v0, 1.0
	v_rcp_f32_e32 v188, v0
	v_mul_f32_e32 v43, v2, v43
	v_mul_f32_e32 v187, v0, v186
	v_fma_f32 v186, -v0, v186, 1.0
	v_lshlrev_b32_e32 v0, 16, v39
	v_mul_f32_e32 v0, 0xbfb8aa3b, v0
	v_exp_f32_e32 v0, v0
	v_cndmask_b32_e64 v188, v188, 1.0, s[58:59]
	v_mul_f32_e32 v41, v41, v188
	v_mul_f32_e32 v187, v185, v187
	v_min_f32_e32 v0, 0x7149f2ca, v0
	v_add_f32_e32 v39, 1.0, v0
	v_fma_f32 v0, v183, v0, 1.0
	v_rcp_f32_e32 v188, v39
	v_rcp_f32_e32 v190, v0
	v_mul_f32_e32 v41, v43, v41
	v_mul_f32_e32 v189, v0, v188
	v_cndmask_b32_e64 v190, v190, 1.0, s[58:59]
	v_mul_f32_e32 v39, v39, v190
	v_mul_f32_e32 v189, v187, v189
	v_fma_f32 v188, -v0, v188, 1.0
	v_mul_f32_e32 v39, v41, v39
	ds_bpermute_b32 v0, v57, v189
	ds_bpermute_b32 v190, v57, v39
	s_waitcnt lgkmcnt(1)
	v_mul_f32_e32 v0, v189, v0
	v_cndmask_b32_e64 v0, v189, v0, s[40:41]
	s_waitcnt lgkmcnt(0)
	v_mul_f32_e32 v190, v39, v190
	v_cndmask_b32_e64 v190, v39, v190, s[40:41]
	ds_bpermute_b32 v191, v59, v0
	ds_bpermute_b32 v192, v59, v190
	s_waitcnt lgkmcnt(1)
	v_mul_f32_e32 v191, v0, v191
	v_cndmask_b32_e64 v0, v0, v191, s[42:43]
	s_waitcnt lgkmcnt(0)
	v_mul_f32_e32 v191, v190, v192
	v_cndmask_b32_e64 v190, v190, v191, s[42:43]
	ds_bpermute_b32 v190, v57, v190
	ds_bpermute_b32 v191, v57, v0
	ds_bpermute_b32 v0, v61, v0
	s_waitcnt lgkmcnt(2)
	v_cndmask_b32_e64 v190, 1.0, v190, s[40:41]
	v_mul_f32_e32 v2, v2, v190
	s_waitcnt lgkmcnt(1)
	v_cndmask_b32_e64 v191, 1.0, v191, s[40:41]
	v_min_f32_e32 v2, 0x799a130c, v2
	v_mul_f32_e32 v2, v44, v2
	v_mul_f32_e32 v44, v45, v191
	v_mul_f32_e32 v1, v44, v1
	v_cvt_pk_bf16_f32 v1, v1, s0
	v_lshl_add_u32 v44, v140, 1, s80
	ds_write_b16 v44, v1 offset:22528
	v_cvt_pk_bf16_f32 v1, v2, s0
	ds_write_b16 v44, v1 offset:26880
	s_waitcnt lgkmcnt(2)
	v_mul_f32_e32 v1, v2, v0
	v_lshlrev_b32_e32 v2, 1, v54
	v_cvt_pk_bf16_f32 v1, v1, s0
	v_add3_u32 v2, s80, v63, v2
	ds_write_b16 v2, v1 offset:31232
	v_mul_f32_e32 v1, v43, v190
	v_mul_f32_e32 v43, v185, v191
	v_min_f32_e32 v1, 0x799a130c, v1
	v_mul_f32_e32 v42, v43, v42
	v_mul_f32_e32 v1, v184, v1
	v_cvt_pk_bf16_f32 v42, v42, s0
	v_lshl_add_u32 v43, v140, 1, s80
	ds_write_b16 v43, v42 offset:22800
	v_cvt_pk_bf16_f32 v42, v1, s0
	v_mul_f32_e32 v1, v1, v0
	v_cvt_pk_bf16_f32 v1, v1, s0
	ds_write_b16 v43, v42 offset:27152
	ds_write_b16 v2, v1 offset:31234
	v_mul_f32_e32 v1, v41, v190
	v_mul_f32_e32 v41, v187, v191
	v_min_f32_e32 v1, 0x799a130c, v1
	v_mul_f32_e32 v40, v41, v40
	v_mul_f32_e32 v1, v186, v1
	v_cvt_pk_bf16_f32 v40, v40, s0
	v_lshl_add_u32 v41, v140, 1, s80
	ds_write_b16 v41, v40 offset:23072
	v_cvt_pk_bf16_f32 v40, v1, s0
	v_mul_f32_e32 v1, v1, v0
	v_cvt_pk_bf16_f32 v1, v1, s0
	ds_write_b16 v41, v40 offset:27424
	ds_write_b16 v2, v1 offset:31236
	v_mul_f32_e32 v1, v39, v190
	v_mul_f32_e32 v39, v189, v191
	v_min_f32_e32 v1, 0x799a130c, v1
	v_mul_f32_e32 v38, v39, v38
	v_mul_f32_e32 v1, v188, v1
	v_cvt_pk_bf16_f32 v38, v38, s0
	v_lshl_add_u32 v39, v140, 1, s80
	ds_write_b16 v39, v38 offset:23344
	v_cvt_pk_bf16_f32 v38, v1, s0
	v_mul_f32_e32 v1, v1, v0
	v_cvt_pk_bf16_f32 v1, v1, s0
	ds_write_b16 v39, v38 offset:27696
	ds_write_b16 v2, v1 offset:31238
	s_and_saveexec_b64 s[12:13], s[44:45]
	v_lshl_add_u32 v1, v52, 2, s80
	ds_write_b32 v1, v0 offset:43520
	s_or_b64 exec, exec, s[12:13]
	v_lshl_add_u32 v0, v67, 1, s80
	ds_write_b16 v0, v36 offset:37376
	ds_write_b16_d16_hi v0, v36 offset:37424
	ds_write_b16 v0, v37 offset:37472
	ds_write_b16_d16_hi v0, v37 offset:37520
.LBB0_950:
	v_lshlrev_b32_e32 v0, 1, v135
	v_lshlrev_b32_e32 v1, 1, v154
	v_add3_u32 v2, s62, v0, v1
	v_add_u32_e32 v207, s62, v63
	v_lshl_add_u32 v227, v54, 1, v207
	v_add_u32_e32 v0, v2, v176
	ds_read_b128 v[36:39], v2 offset:4352
	ds_read_b128 v[40:43], v2
	ds_read_b128 v[208:211], v2 offset:4416
	ds_read_b128 v[184:187], v2 offset:64
	ds_read_b128 v[212:215], v2 offset:4480
	ds_read_b128 v[228:231], v2 offset:128
	ds_read_b128 v[232:235], v2 offset:4544
	ds_read_b128 v[236:239], v2 offset:192
	ds_read_b64 v[188:189], v227 offset:14848
	ds_read2_b64 v[240:243], v0 offset1:4
	ds_read2_b64 v[244:247], v0 offset0:8 offset1:12
	s_and_b64 s[12:13], s[54:55], s[52:53]
	v_mov_b32_e32 v190, v3
	v_mov_b32_e32 v191, v3
	s_waitcnt lgkmcnt(9)
	v_mfma_f32_16x16x32_bf16 v[36:39], v[36:39], v[40:43], 0
	s_waitcnt lgkmcnt(7)
	v_mfma_f32_16x16x32_bf16 v[36:39], v[208:211], v[184:187], v[36:39]
	s_waitcnt lgkmcnt(5)
	v_mfma_f32_16x16x32_bf16 v[36:39], v[212:215], v[228:231], v[36:39]
	s_waitcnt lgkmcnt(3)
	v_mfma_f32_16x16x32_bf16 v[36:39], v[232:235], v[236:239], v[36:39]
	ds_read2_b64 v[208:211], v0 offset0:16 offset1:20
	ds_read2_b64 v[212:215], v0 offset0:24 offset1:28
	v_cvt_pk_bf16_f32 v184, v4, v5
	v_cvt_pk_bf16_f32 v185, v6, v7
	v_cvt_pk_bf16_f32 v186, v8, v9
	v_cvt_pk_bf16_f32 v187, v10, v11
	v_mov_b32_e32 v2, v3
	s_nop 0
	v_cndmask_b32_e64 v192, v38, 0, s[12:13]
	s_and_b64 s[12:13], s[12:13], s[50:51]
	v_cndmask_b32_e64 v0, v37, 0, s[12:13]
	s_and_b64 s[12:13], s[12:13], s[48:49]
	v_cndmask_b32_e64 v36, v36, 0, s[12:13]
	v_cndmask_b32_e64 v1, v39, 0, s[54:55]
	v_cvt_pk_bf16_f32 v0, v36, v0
	v_cvt_pk_bf16_f32 v1, v192, v1
	s_nop 0
	s_waitcnt lgkmcnt(4)
	v_mfma_f32_16x16x32_bf16 v[36:39], v[188:191], v[0:3], 0
	v_cvt_pk_bf16_f32 v40, v12, v13
	v_cvt_pk_bf16_f32 v41, v14, v15
	v_cvt_pk_bf16_f32 v42, v16, v17
	v_cvt_pk_bf16_f32 v43, v18, v19
	v_cvt_pk_bf16_f32 v228, v20, v21
	v_cvt_pk_bf16_f32 v229, v22, v23
	v_cvt_pk_bf16_f32 v230, v24, v25
	v_cvt_pk_bf16_f32 v231, v26, v27
	v_cvt_pk_bf16_f32 v232, v28, v29
	v_cvt_pk_bf16_f32 v233, v30, v31
	v_cvt_pk_bf16_f32 v234, v32, v33
	v_cvt_pk_bf16_f32 v235, v34, v35
	s_waitcnt lgkmcnt(3)
	v_mfma_f32_16x16x32_bf16 v[36:39], v[184:187], v[240:243], v[36:39]
	s_waitcnt lgkmcnt(2)
	v_mfma_f32_16x16x32_bf16 v[36:39], v[40:43], v[244:247], v[36:39]
	s_waitcnt lgkmcnt(1)
	v_mfma_f32_16x16x32_bf16 v[36:39], v[228:231], v[208:211], v[36:39]
	s_waitcnt lgkmcnt(0)
	v_mfma_f32_16x16x32_bf16 v[36:39], v[232:235], v[212:215], v[36:39]
	v_add_u32_e32 v227, v207, v155
	v_add_u32_e32 v216, s62, v142
	v_add3_u32 v217, s62, v155, v156
	v_mov_b32_e32 v32, 0
	v_mov_b32_e32 v33, 0
	v_mov_b32_e32 v34, 0
	v_mov_b32_e32 v35, 0
	s_and_saveexec_b64 s[12:13], s[46:47]
	ds_read_b128 v[32:35], v227 offset:14848
	s_or_b64 exec, exec, s[12:13]
	ds_read_b64 v[240:241], v216 offset:20992
	ds_read_b128 v[184:187], v217 offset:8704
	ds_read_b128 v[40:43], v217 offset:9472
	ds_read_b128 v[228:231], v217 offset:10240
	ds_read_b128 v[232:235], v217 offset:11008
	s_ashr_i32 s12, s32, 4
	s_add_i32 s12, s12, -2
	v_sub_u32_e32 v0, v51, v54
	v_cvt_pk_bf16_f32 v192, v36, v37
	v_cvt_pk_bf16_f32 v193, v38, v39
	v_mad_i32_i24 v0, v0, s12, v197
	global_store_dwordx2 v0, v[192:193], s[100:101]
	s_waitcnt lgkmcnt(3)
	v_mul_f32_dpp v4, v240, v4 row_newbcast:0 row_mask:0xf bank_mask:0xf
	v_mul_f32_dpp v5, v241, v5 row_newbcast:0 row_mask:0xf bank_mask:0xf
	v_mul_f32_dpp v6, v240, v6 row_newbcast:1 row_mask:0xf bank_mask:0xf
	v_mul_f32_dpp v7, v241, v7 row_newbcast:1 row_mask:0xf bank_mask:0xf
	s_nop 1
	v_mfma_f32_16x16x32_bf16 v[4:7], v[184:187], v[32:35], v[4:7]
	ds_read_b128 v[184:187], v217 offset:11776
	s_waitcnt lgkmcnt(3)
	v_mul_f32_dpp v8, v240, v8 row_newbcast:2 row_mask:0xf bank_mask:0xf
	v_mul_f32_dpp v9, v241, v9 row_newbcast:2 row_mask:0xf bank_mask:0xf
	v_mul_f32_dpp v10, v240, v10 row_newbcast:3 row_mask:0xf bank_mask:0xf
	v_mul_f32_dpp v11, v241, v11 row_newbcast:3 row_mask:0xf bank_mask:0xf
	s_nop 1
	v_mfma_f32_16x16x32_bf16 v[8:11], v[40:43], v[32:35], v[8:11]
	ds_read_b128 v[40:43], v217 offset:12544
	s_waitcnt lgkmcnt(3)
	v_mul_f32_dpp v12, v240, v12 row_newbcast:4 row_mask:0xf bank_mask:0xf
	v_mul_f32_dpp v13, v241, v13 row_newbcast:4 row_mask:0xf bank_mask:0xf
	v_mul_f32_dpp v14, v240, v14 row_newbcast:5 row_mask:0xf bank_mask:0xf
	v_mul_f32_dpp v15, v241, v15 row_newbcast:5 row_mask:0xf bank_mask:0xf
	s_nop 1
	v_mfma_f32_16x16x32_bf16 v[12:15], v[228:231], v[32:35], v[12:15]
	ds_read_b128 v[228:231], v217 offset:13312
	s_waitcnt lgkmcnt(3)
	v_mul_f32_dpp v16, v240, v16 row_newbcast:6 row_mask:0xf bank_mask:0xf
	v_mul_f32_dpp v17, v241, v17 row_newbcast:6 row_mask:0xf bank_mask:0xf
	v_mul_f32_dpp v18, v240, v18 row_newbcast:7 row_mask:0xf bank_mask:0xf
	v_mul_f32_dpp v19, v241, v19 row_newbcast:7 row_mask:0xf bank_mask:0xf
	s_nop 1
	v_mfma_f32_16x16x32_bf16 v[16:19], v[232:235], v[32:35], v[16:19]
	ds_read_b128 v[232:235], v217 offset:14080
	s_waitcnt lgkmcnt(3)
	v_mul_f32_dpp v20, v240, v20 row_newbcast:8 row_mask:0xf bank_mask:0xf
	v_mul_f32_dpp v21, v241, v21 row_newbcast:8 row_mask:0xf bank_mask:0xf
	v_mul_f32_dpp v22, v240, v22 row_newbcast:9 row_mask:0xf bank_mask:0xf
	v_mul_f32_dpp v23, v241, v23 row_newbcast:9 row_mask:0xf bank_mask:0xf
	s_nop 1
	v_mfma_f32_16x16x32_bf16 v[20:23], v[184:187], v[32:35], v[20:23]
	s_waitcnt lgkmcnt(2)
	v_mul_f32_dpp v24, v240, v24 row_newbcast:10 row_mask:0xf bank_mask:0xf
	v_mul_f32_dpp v25, v241, v25 row_newbcast:10 row_mask:0xf bank_mask:0xf
	v_mul_f32_dpp v26, v240, v26 row_newbcast:11 row_mask:0xf bank_mask:0xf
	v_mul_f32_dpp v27, v241, v27 row_newbcast:11 row_mask:0xf bank_mask:0xf
	s_nop 1
	v_mfma_f32_16x16x32_bf16 v[24:27], v[40:43], v[32:35], v[24:27]
	s_waitcnt lgkmcnt(1)
	v_mul_f32_dpp v28, v240, v28 row_newbcast:12 row_mask:0xf bank_mask:0xf
	v_mul_f32_dpp v29, v241, v29 row_newbcast:12 row_mask:0xf bank_mask:0xf
	v_mul_f32_dpp v30, v240, v30 row_newbcast:13 row_mask:0xf bank_mask:0xf
	v_mul_f32_dpp v31, v241, v31 row_newbcast:13 row_mask:0xf bank_mask:0xf
	s_nop 1
	v_mfma_f32_16x16x32_bf16 v[28:31], v[228:231], v[32:35], v[28:31]
	s_waitcnt lgkmcnt(0)
	v_mul_f32_dpp v212, v240, v148 row_newbcast:14 row_mask:0xf bank_mask:0xf
	v_mul_f32_dpp v213, v241, v149 row_newbcast:14 row_mask:0xf bank_mask:0xf
	v_mul_f32_dpp v214, v240, v150 row_newbcast:15 row_mask:0xf bank_mask:0xf
	v_mul_f32_dpp v215, v241, v151 row_newbcast:15 row_mask:0xf bank_mask:0xf
	s_nop 1
	v_mfma_f32_16x16x32_bf16 v[32:35], v[232:235], v[32:35], v[212:215]
	v_add_u32_e32 v197, s32, v197
	v_add_u32_e32 v198, s32, v198
	v_add_u32_e32 v248, s32, v248
	v_add_u32_e32 v249, s32, v249
	v_lshl_add_u64 v[48:49], v[48:49], 0, v[46:47]
	s_add_i32 s60, s60, 16
	s_add_i32 s61, s61, 1
	s_cmpk_lg_i32 s60, 0x100
	s_barrier
	s_cbranch_scc1 .LBB0_943
	s_mov_b64 s[58:59], -1
	s_branch .LBB0_1005
.Lhc_alt_top:
	s_nop 2
	v_mov_b32_e32 v148, v32
	v_mov_b32_e32 v149, v33
	v_mov_b32_e32 v150, v34
	v_mov_b32_e32 v151, v35
	s_bitcmp1_b32 s61, 0
	s_cselect_b32 s62, 0x5800, 0
	v_lshlrev_b32_e32 v0, 1, v135
	v_lshlrev_b32_e32 v1, 1, v154
	v_add3_u32 v2, s62, v0, v1
	v_add_u32_e32 v207, s62, v63
	v_lshl_add_u32 v227, v54, 1, v207
	v_add_u32_e32 v0, v2, v176
	ds_read_b128 v[36:39], v2 offset:4352
	ds_read_b128 v[40:43], v2
	ds_read_b128 v[208:211], v2 offset:4416
	ds_read_b128 v[184:187], v2 offset:64
	ds_read_b128 v[212:215], v2 offset:4480
	ds_read_b128 v[228:231], v2 offset:128
	ds_read_b128 v[232:235], v2 offset:4544
	ds_read_b128 v[236:239], v2 offset:192
	ds_read_b64 v[188:189], v227 offset:14848
	ds_read2_b64 v[240:243], v0 offset1:4
	ds_read2_b64 v[244:247], v0 offset0:8 offset1:12
	s_and_b64 s[12:13], s[54:55], s[52:53]
	v_mov_b32_e32 v190, v3
	v_mov_b32_e32 v191, v3
	s_waitcnt lgkmcnt(9)
	v_mfma_f32_16x16x32_bf16 v[36:39], v[36:39], v[40:43], 0
	s_waitcnt lgkmcnt(7)
	v_mfma_f32_16x16x32_bf16 v[36:39], v[208:211], v[184:187], v[36:39]
	s_waitcnt lgkmcnt(5)
	v_mfma_f32_16x16x32_bf16 v[36:39], v[212:215], v[228:231], v[36:39]
	s_waitcnt lgkmcnt(3)
	v_mfma_f32_16x16x32_bf16 v[36:39], v[232:235], v[236:239], v[36:39]
	ds_read2_b64 v[208:211], v0 offset0:16 offset1:20
	ds_read2_b64 v[212:215], v0 offset0:24 offset1:28
	v_cvt_pk_bf16_f32 v184, v4, v5
	v_cvt_pk_bf16_f32 v185, v6, v7
	v_cvt_pk_bf16_f32 v186, v8, v9
	v_cvt_pk_bf16_f32 v187, v10, v11
	v_mov_b32_e32 v2, v3
	s_nop 0
	v_cndmask_b32_e64 v192, v38, 0, s[12:13]
	s_and_b64 s[12:13], s[12:13], s[50:51]
	v_cndmask_b32_e64 v0, v37, 0, s[12:13]
	s_and_b64 s[12:13], s[12:13], s[48:49]
	v_cndmask_b32_e64 v36, v36, 0, s[12:13]
	v_cndmask_b32_e64 v1, v39, 0, s[54:55]
	v_cvt_pk_bf16_f32 v0, v36, v0
	v_cvt_pk_bf16_f32 v1, v192, v1
	s_nop 0
	s_waitcnt lgkmcnt(4)
	v_mfma_f32_16x16x32_bf16 v[36:39], v[188:191], v[0:3], 0
	v_cvt_pk_bf16_f32 v40, v12, v13
	v_cvt_pk_bf16_f32 v41, v14, v15
	v_cvt_pk_bf16_f32 v42, v16, v17
	v_cvt_pk_bf16_f32 v43, v18, v19
	v_cvt_pk_bf16_f32 v228, v20, v21
	v_cvt_pk_bf16_f32 v229, v22, v23
	v_cvt_pk_bf16_f32 v230, v24, v25
	v_cvt_pk_bf16_f32 v231, v26, v27
	v_cvt_pk_bf16_f32 v232, v28, v29
	v_cvt_pk_bf16_f32 v233, v30, v31
	v_cvt_pk_bf16_f32 v234, v32, v33
	v_cvt_pk_bf16_f32 v235, v34, v35
	s_waitcnt lgkmcnt(3)
	v_mfma_f32_16x16x32_bf16 v[36:39], v[184:187], v[240:243], v[36:39]
	s_waitcnt lgkmcnt(2)
	v_mfma_f32_16x16x32_bf16 v[36:39], v[40:43], v[244:247], v[36:39]
	s_waitcnt lgkmcnt(1)
	v_mfma_f32_16x16x32_bf16 v[36:39], v[228:231], v[208:211], v[36:39]
	s_waitcnt lgkmcnt(0)
	v_mfma_f32_16x16x32_bf16 v[36:39], v[232:235], v[212:215], v[36:39]
	v_add_u32_e32 v227, v207, v155
	v_add_u32_e32 v216, s62, v142
	v_add3_u32 v217, s62, v155, v156
	v_mov_b32_e32 v32, 0
	v_mov_b32_e32 v33, 0
	v_mov_b32_e32 v34, 0
	v_mov_b32_e32 v35, 0
	s_and_saveexec_b64 s[12:13], s[46:47]
	ds_read_b128 v[32:35], v227 offset:14848
	s_or_b64 exec, exec, s[12:13]
	ds_read_b64 v[240:241], v216 offset:20992
	ds_read_b128 v[184:187], v217 offset:8704
	ds_read_b128 v[40:43], v217 offset:9472
	ds_read_b128 v[228:231], v217 offset:10240
	ds_read_b128 v[232:235], v217 offset:11008
	s_ashr_i32 s12, s32, 4
	s_add_i32 s12, s12, -2
	v_sub_u32_e32 v0, v51, v54
	v_cvt_pk_bf16_f32 v192, v36, v37
	v_cvt_pk_bf16_f32 v193, v38, v39
	v_mad_i32_i24 v0, v0, s12, v197
	global_store_dwordx2 v0, v[192:193], s[100:101]
	s_waitcnt lgkmcnt(3)
	v_mul_f32_dpp v4, v240, v4 row_newbcast:0 row_mask:0xf bank_mask:0xf
	v_mul_f32_dpp v5, v241, v5 row_newbcast:0 row_mask:0xf bank_mask:0xf
	v_mul_f32_dpp v6, v240, v6 row_newbcast:1 row_mask:0xf bank_mask:0xf
	v_mul_f32_dpp v7, v241, v7 row_newbcast:1 row_mask:0xf bank_mask:0xf
	s_nop 1
	v_mfma_f32_16x16x32_bf16 v[4:7], v[184:187], v[32:35], v[4:7]
	ds_read_b128 v[184:187], v217 offset:11776
	s_waitcnt lgkmcnt(3)
	v_mul_f32_dpp v8, v240, v8 row_newbcast:2 row_mask:0xf bank_mask:0xf
	v_mul_f32_dpp v9, v241, v9 row_newbcast:2 row_mask:0xf bank_mask:0xf
	v_mul_f32_dpp v10, v240, v10 row_newbcast:3 row_mask:0xf bank_mask:0xf
	v_mul_f32_dpp v11, v241, v11 row_newbcast:3 row_mask:0xf bank_mask:0xf
	s_nop 1
	v_mfma_f32_16x16x32_bf16 v[8:11], v[40:43], v[32:35], v[8:11]
	ds_read_b128 v[40:43], v217 offset:12544
	s_waitcnt lgkmcnt(3)
	v_mul_f32_dpp v12, v240, v12 row_newbcast:4 row_mask:0xf bank_mask:0xf
	v_mul_f32_dpp v13, v241, v13 row_newbcast:4 row_mask:0xf bank_mask:0xf
	v_mul_f32_dpp v14, v240, v14 row_newbcast:5 row_mask:0xf bank_mask:0xf
	v_mul_f32_dpp v15, v241, v15 row_newbcast:5 row_mask:0xf bank_mask:0xf
	s_nop 1
	v_mfma_f32_16x16x32_bf16 v[12:15], v[228:231], v[32:35], v[12:15]
	ds_read_b128 v[228:231], v217 offset:13312
	s_waitcnt lgkmcnt(3)
	v_mul_f32_dpp v16, v240, v16 row_newbcast:6 row_mask:0xf bank_mask:0xf
	v_mul_f32_dpp v17, v241, v17 row_newbcast:6 row_mask:0xf bank_mask:0xf
	v_mul_f32_dpp v18, v240, v18 row_newbcast:7 row_mask:0xf bank_mask:0xf
	v_mul_f32_dpp v19, v241, v19 row_newbcast:7 row_mask:0xf bank_mask:0xf
	s_nop 1
	v_mfma_f32_16x16x32_bf16 v[16:19], v[232:235], v[32:35], v[16:19]
	ds_read_b128 v[232:235], v217 offset:14080
	s_waitcnt lgkmcnt(3)
	v_mul_f32_dpp v20, v240, v20 row_newbcast:8 row_mask:0xf bank_mask:0xf
	v_mul_f32_dpp v21, v241, v21 row_newbcast:8 row_mask:0xf bank_mask:0xf
	v_mul_f32_dpp v22, v240, v22 row_newbcast:9 row_mask:0xf bank_mask:0xf
	v_mul_f32_dpp v23, v241, v23 row_newbcast:9 row_mask:0xf bank_mask:0xf
	s_nop 1
	v_mfma_f32_16x16x32_bf16 v[20:23], v[184:187], v[32:35], v[20:23]
	s_waitcnt lgkmcnt(2)
	v_mul_f32_dpp v24, v240, v24 row_newbcast:10 row_mask:0xf bank_mask:0xf
	v_mul_f32_dpp v25, v241, v25 row_newbcast:10 row_mask:0xf bank_mask:0xf
	v_mul_f32_dpp v26, v240, v26 row_newbcast:11 row_mask:0xf bank_mask:0xf
	v_mul_f32_dpp v27, v241, v27 row_newbcast:11 row_mask:0xf bank_mask:0xf
	s_nop 1
	v_mfma_f32_16x16x32_bf16 v[24:27], v[40:43], v[32:35], v[24:27]
	s_waitcnt lgkmcnt(1)
	v_mul_f32_dpp v28, v240, v28 row_newbcast:12 row_mask:0xf bank_mask:0xf
	v_mul_f32_dpp v29, v241, v29 row_newbcast:12 row_mask:0xf bank_mask:0xf
	v_mul_f32_dpp v30, v240, v30 row_newbcast:13 row_mask:0xf bank_mask:0xf
	v_mul_f32_dpp v31, v241, v31 row_newbcast:13 row_mask:0xf bank_mask:0xf
	s_nop 1
	v_mfma_f32_16x16x32_bf16 v[28:31], v[228:231], v[32:35], v[28:31]
	s_waitcnt lgkmcnt(0)
	v_mul_f32_dpp v212, v240, v148 row_newbcast:14 row_mask:0xf bank_mask:0xf
	v_mul_f32_dpp v213, v241, v149 row_newbcast:14 row_mask:0xf bank_mask:0xf
	v_mul_f32_dpp v214, v240, v150 row_newbcast:15 row_mask:0xf bank_mask:0xf
	v_mul_f32_dpp v215, v241, v151 row_newbcast:15 row_mask:0xf bank_mask:0xf
	s_nop 1
	v_mfma_f32_16x16x32_bf16 v[32:35], v[232:235], v[32:35], v[212:215]
	s_cmp_gt_u32 s61, 14
	s_cbranch_scc1 .Lhc_alt_tail
	s_waitcnt vmcnt(1)
	v_mov_b32_e32 v44, v200
	v_mov_b32_e32 v42, v202
	v_mov_b32_e32 v40, v204
	v_mov_b32_e32 v38, v206
	v_mov_b32_e32 v45, v199
	v_mov_b32_e32 v43, v201
	v_mov_b32_e32 v41, v203
	v_mov_b32_e32 v39, v205
	v_mov_b64_e32 v[36:37], v[152:153]
	s_cmpk_eq_i32 s60, 0xe0
	s_cbranch_scc1 .Lhc_alt_947
	global_load_ushort v199, v197, s[24:25]
	global_load_ushort v200, v197, s[98:99]
	global_load_ushort v201, v198, s[24:25]
	global_load_ushort v202, v198, s[98:99]
	global_load_ushort v203, v248, s[24:25]
	global_load_ushort v204, v248, s[98:99]
	global_load_ushort v205, v249, s[24:25]
	global_load_ushort v206, v249, s[98:99]
	global_load_dwordx2 v[152:153], v[48:49], off

.LBB0_982:
	v_lshlrev_b32_e32 v43, 16, v205
	v_mul_f32_e32 v43, 0xbfb8aa3b, v43
	v_exp_f32_e32 v43, v43
	v_lshlrev_b32_e32 v44, 16, v206
	s_sub_i32 s83, 0, s82
	v_min_f32_e32 v43, 0x7149f2ca, v43
	v_add_f32_e32 v45, 1.0, v43
	v_rcp_f32_e32 v46, v45
	v_fma_f32 v43, v183, v43, 1.0
	v_rcp_f32_e32 v48, v43
	v_mul_f32_e32 v47, v43, v46
	v_fma_f32 v46, -v43, v46, 1.0
	v_lshlrev_b32_e32 v43, 16, v203
	v_mul_f32_e32 v43, 0xbfb8aa3b, v43
	v_exp_f32_e32 v43, v43
	v_cndmask_b32_e64 v48, v48, 1.0, s[56:57]
	v_mul_f32_e32 v45, v45, v48
	v_lshlrev_b32_e32 v48, 16, v204
	v_min_f32_e32 v43, 0x7149f2ca, v43
	v_add_f32_e32 v49, 1.0, v43
	v_rcp_f32_e32 v184, v49
	v_fma_f32 v43, v183, v43, 1.0
	v_rcp_f32_e32 v186, v43
	v_mul_f32_e32 v185, v43, v184
	v_fma_f32 v184, -v43, v184, 1.0
	v_lshlrev_b32_e32 v43, 16, v201
	v_mul_f32_e32 v43, 0xbfb8aa3b, v43
	v_exp_f32_e32 v43, v43
	v_cndmask_b32_e64 v186, v186, 1.0, s[56:57]
	v_mul_f32_e32 v49, v49, v186
	v_mul_f32_e32 v185, v47, v185
	v_min_f32_e32 v43, 0x7149f2ca, v43
	v_add_f32_e32 v187, 1.0, v43
	v_rcp_f32_e32 v188, v187
	v_fma_f32 v43, v183, v43, 1.0
	v_rcp_f32_e32 v190, v43
	v_mul_f32_e32 v49, v45, v49
	v_mul_f32_e32 v189, v43, v188
	v_fma_f32 v188, -v43, v188, 1.0
	v_lshlrev_b32_e32 v43, 16, v199
	v_mul_f32_e32 v43, 0xbfb8aa3b, v43
	v_exp_f32_e32 v43, v43
	v_cndmask_b32_e64 v190, v190, 1.0, s[56:57]
	v_mul_f32_e32 v187, v187, v190
	v_mul_f32_e32 v189, v185, v189
	v_min_f32_e32 v43, 0x7149f2ca, v43
	v_add_f32_e32 v191, 1.0, v43
	v_fma_f32 v43, v183, v43, 1.0
	v_rcp_f32_e32 v192, v191
	v_rcp_f32_e32 v194, v43
	v_mul_f32_e32 v187, v49, v187
	v_lshlrev_b32_e32 v186, 16, v202
	v_mul_f32_e32 v193, v43, v192
	v_cndmask_b32_e64 v194, v194, 1.0, s[56:57]
	v_mul_f32_e32 v191, v191, v194
	v_mul_f32_e32 v193, v189, v193
	v_fma_f32 v192, -v43, v192, 1.0
	v_mul_f32_e32 v191, v187, v191
	ds_bpermute_b32 v43, v57, v193
	ds_bpermute_b32 v194, v57, v191
	v_lshlrev_b32_e32 v190, 16, v200
	s_waitcnt lgkmcnt(1)
	v_mul_f32_e32 v43, v193, v43
	v_cndmask_b32_e64 v43, v193, v43, s[40:41]
	s_waitcnt lgkmcnt(0)
	v_mul_f32_e32 v194, v191, v194
	v_cndmask_b32_e64 v194, v191, v194, s[40:41]
	ds_bpermute_b32 v195, v59, v43
	ds_bpermute_b32 v196, v59, v194
	s_waitcnt lgkmcnt(1)
	v_mul_f32_e32 v195, v43, v195
	v_cndmask_b32_e64 v43, v43, v195, s[42:43]
	s_waitcnt lgkmcnt(0)
	v_mul_f32_e32 v195, v194, v196
	v_cndmask_b32_e64 v194, v194, v195, s[42:43]
	ds_bpermute_b32 v194, v57, v194
	ds_bpermute_b32 v195, v57, v43
	ds_bpermute_b32 v43, v61, v43
	s_waitcnt lgkmcnt(2)
	v_cndmask_b32_e64 v194, 1.0, v194, s[40:41]
	v_mul_f32_e32 v45, v45, v194
	s_waitcnt lgkmcnt(1)
	v_cndmask_b32_e64 v195, 1.0, v195, s[40:41]
	v_min_f32_e32 v45, 0x799a130c, v45
	v_mul_f32_e32 v45, v46, v45
	v_mul_f32_e32 v46, v47, v195
	v_mul_f32_e32 v44, v46, v44
	v_cvt_pk_bf16_f32 v44, v44, s0
	v_lshl_add_u32 v46, v140, 1, s83
	ds_write_b16 v46, v44 offset:22528
	v_cvt_pk_bf16_f32 v44, v45, s0
	ds_write_b16 v46, v44 offset:26880
	s_waitcnt lgkmcnt(2)
	v_mul_f32_e32 v44, v45, v43
	v_lshlrev_b32_e32 v45, 1, v54
	v_cvt_pk_bf16_f32 v44, v44, s0
	v_add3_u32 v45, s83, v63, v45
	ds_write_b16 v45, v44 offset:31232
	v_mul_f32_e32 v44, v49, v194
	v_mul_f32_e32 v46, v185, v195
	v_min_f32_e32 v44, 0x799a130c, v44
	v_mul_f32_e32 v46, v46, v48
	v_mul_f32_e32 v44, v184, v44
	v_cvt_pk_bf16_f32 v46, v46, s0
	v_lshl_add_u32 v47, v140, 1, s83
	ds_write_b16 v47, v46 offset:22800
	v_cvt_pk_bf16_f32 v46, v44, s0
	v_mul_f32_e32 v44, v44, v43
	v_cvt_pk_bf16_f32 v44, v44, s0
	ds_write_b16 v47, v46 offset:27152
	ds_write_b16 v45, v44 offset:31234
	v_mul_f32_e32 v44, v187, v194
	v_mul_f32_e32 v46, v189, v195
	v_min_f32_e32 v44, 0x799a130c, v44
	v_mul_f32_e32 v46, v46, v186
	v_mul_f32_e32 v44, v188, v44
	v_cvt_pk_bf16_f32 v46, v46, s0
	v_lshl_add_u32 v47, v140, 1, s83
	ds_write_b16 v47, v46 offset:23072
	v_cvt_pk_bf16_f32 v46, v44, s0
	v_mul_f32_e32 v44, v44, v43
	v_cvt_pk_bf16_f32 v44, v44, s0
	ds_write_b16 v47, v46 offset:27424
	ds_write_b16 v45, v44 offset:31236
	v_mul_f32_e32 v44, v191, v194
	v_mul_f32_e32 v46, v193, v195
	v_min_f32_e32 v44, 0x799a130c, v44
	v_mul_f32_e32 v46, v46, v190
	v_mul_f32_e32 v44, v192, v44
	v_cvt_pk_bf16_f32 v46, v46, s0
	v_lshl_add_u32 v47, v140, 1, s83
	ds_write_b16 v47, v46 offset:23344
	v_cvt_pk_bf16_f32 v46, v44, s0
	v_mul_f32_e32 v44, v44, v43
	v_cvt_pk_bf16_f32 v44, v44, s0
	ds_write_b16 v47, v46 offset:27696
	ds_write_b16 v45, v44 offset:31238
	s_and_saveexec_b64 s[14:15], s[44:45]
	v_lshl_add_u32 v44, v52, 2, s83
	ds_write_b32 v44, v43 offset:43520
	s_or_b64 exec, exec, s[14:15]
	v_lshl_add_u32 v43, v67, 1, s83
	ds_write_b16 v43, v148 offset:37376
	ds_write_b16_d16_hi v43, v148 offset:37424
	ds_write_b16 v43, v149 offset:37472
	ds_write_b16_d16_hi v43, v149 offset:37520
.LBB0_985:
	v_lshlrev_b32_e32 v0, 1, v135
	v_lshlrev_b32_e32 v1, 1, v154
	v_add3_u32 v2, s82, v0, v1
	v_add_u32_e32 v207, s82, v63
	v_lshl_add_u32 v227, v54, 1, v207
	v_add_u32_e32 v0, v2, v176
	ds_read_b128 v[36:39], v2 offset:4352
	ds_read_b128 v[40:43], v2
	ds_read_b128 v[208:211], v2 offset:4416
	ds_read_b128 v[184:187], v2 offset:64
	ds_read_b128 v[212:215], v2 offset:4480
	ds_read_b128 v[228:231], v2 offset:128
	ds_read_b128 v[232:235], v2 offset:4544
	ds_read_b128 v[236:239], v2 offset:192
	ds_read_b64 v[188:189], v227 offset:14848
	ds_read2_b64 v[240:243], v0 offset1:4
	ds_read2_b64 v[244:247], v0 offset0:8 offset1:12
	s_and_b64 s[14:15], s[54:55], s[52:53]
	v_mov_b32_e32 v190, v3
	v_mov_b32_e32 v191, v3
	s_waitcnt lgkmcnt(9)
	v_mfma_f32_16x16x32_bf16 v[36:39], v[36:39], v[40:43], 0
	s_waitcnt lgkmcnt(7)
	v_mfma_f32_16x16x32_bf16 v[36:39], v[208:211], v[184:187], v[36:39]
	s_waitcnt lgkmcnt(5)
	v_mfma_f32_16x16x32_bf16 v[36:39], v[212:215], v[228:231], v[36:39]
	s_waitcnt lgkmcnt(3)
	v_mfma_f32_16x16x32_bf16 v[36:39], v[232:235], v[236:239], v[36:39]
	ds_read2_b64 v[208:211], v0 offset0:16 offset1:20
	ds_read2_b64 v[212:215], v0 offset0:24 offset1:28
	v_cvt_pk_bf16_f32 v184, v4, v5
	v_cvt_pk_bf16_f32 v185, v6, v7
	v_cvt_pk_bf16_f32 v186, v8, v9
	v_cvt_pk_bf16_f32 v187, v10, v11
	v_mov_b32_e32 v2, v3
	s_nop 0
	v_cndmask_b32_e64 v192, v38, 0, s[14:15]
	s_and_b64 s[14:15], s[14:15], s[50:51]
	v_cndmask_b32_e64 v0, v37, 0, s[14:15]
	s_and_b64 s[14:15], s[14:15], s[48:49]
	v_cndmask_b32_e64 v36, v36, 0, s[14:15]
	v_cndmask_b32_e64 v1, v39, 0, s[54:55]
	v_cvt_pk_bf16_f32 v0, v36, v0
	v_cvt_pk_bf16_f32 v1, v192, v1
	s_nop 0
	s_waitcnt lgkmcnt(4)
	v_mfma_f32_16x16x32_bf16 v[36:39], v[188:191], v[0:3], 0
	v_cvt_pk_bf16_f32 v40, v12, v13
	v_cvt_pk_bf16_f32 v41, v14, v15
	v_cvt_pk_bf16_f32 v42, v16, v17
	v_cvt_pk_bf16_f32 v43, v18, v19
	v_cvt_pk_bf16_f32 v228, v20, v21
	v_cvt_pk_bf16_f32 v229, v22, v23
	v_cvt_pk_bf16_f32 v230, v24, v25
	v_cvt_pk_bf16_f32 v231, v26, v27
	v_cvt_pk_bf16_f32 v232, v28, v29
	v_cvt_pk_bf16_f32 v233, v30, v31
	v_cvt_pk_bf16_f32 v234, v32, v33
	v_cvt_pk_bf16_f32 v235, v34, v35
	s_waitcnt lgkmcnt(3)
	v_mfma_f32_16x16x32_bf16 v[36:39], v[184:187], v[240:243], v[36:39]
	s_waitcnt lgkmcnt(2)
	v_mfma_f32_16x16x32_bf16 v[36:39], v[40:43], v[244:247], v[36:39]
	s_waitcnt lgkmcnt(1)
	v_mfma_f32_16x16x32_bf16 v[36:39], v[228:231], v[208:211], v[36:39]
	s_waitcnt lgkmcnt(0)
	v_mfma_f32_16x16x32_bf16 v[36:39], v[232:235], v[212:215], v[36:39]
	v_add_u32_e32 v227, v207, v155
	v_add_u32_e32 v216, s82, v142
	v_add3_u32 v217, s82, v155, v156
	v_mov_b32_e32 v44, 0
	v_mov_b32_e32 v45, 0
	v_mov_b32_e32 v46, 0
	v_mov_b32_e32 v47, 0
	s_and_saveexec_b64 s[14:15], s[46:47]
	ds_read_b128 v[44:47], v227 offset:14848
	s_or_b64 exec, exec, s[14:15]
	ds_read_b64 v[240:241], v216 offset:20992
	ds_read_b128 v[184:187], v217 offset:8704
	ds_read_b128 v[40:43], v217 offset:9472
	ds_read_b128 v[228:231], v217 offset:10240
	ds_read_b128 v[232:235], v217 offset:11008
	s_ashr_i32 s14, s32, 4
	s_add_i32 s14, s14, -2
	v_sub_u32_e32 v0, v51, v54
	v_cvt_pk_bf16_f32 v192, v36, v37
	v_cvt_pk_bf16_f32 v193, v38, v39
	v_mad_i32_i24 v0, v0, s14, v197
	global_store_dwordx2 v0, v[192:193], s[100:101]
	s_waitcnt lgkmcnt(3)
	v_mul_f32_dpp v4, v240, v4 row_newbcast:0 row_mask:0xf bank_mask:0xf
	v_mul_f32_dpp v5, v241, v5 row_newbcast:0 row_mask:0xf bank_mask:0xf
	v_mul_f32_dpp v6, v240, v6 row_newbcast:1 row_mask:0xf bank_mask:0xf
	v_mul_f32_dpp v7, v241, v7 row_newbcast:1 row_mask:0xf bank_mask:0xf
	s_nop 1
	v_mfma_f32_16x16x32_bf16 v[4:7], v[184:187], v[44:47], v[4:7]
	ds_read_b128 v[184:187], v217 offset:11776
	s_waitcnt lgkmcnt(3)
	v_mul_f32_dpp v8, v240, v8 row_newbcast:2 row_mask:0xf bank_mask:0xf
	v_mul_f32_dpp v9, v241, v9 row_newbcast:2 row_mask:0xf bank_mask:0xf
	v_mul_f32_dpp v10, v240, v10 row_newbcast:3 row_mask:0xf bank_mask:0xf
	v_mul_f32_dpp v11, v241, v11 row_newbcast:3 row_mask:0xf bank_mask:0xf
	s_nop 1
	v_mfma_f32_16x16x32_bf16 v[8:11], v[40:43], v[44:47], v[8:11]
	ds_read_b128 v[40:43], v217 offset:12544
	s_waitcnt lgkmcnt(3)
	v_mul_f32_dpp v12, v240, v12 row_newbcast:4 row_mask:0xf bank_mask:0xf
	v_mul_f32_dpp v13, v241, v13 row_newbcast:4 row_mask:0xf bank_mask:0xf
	v_mul_f32_dpp v14, v240, v14 row_newbcast:5 row_mask:0xf bank_mask:0xf
	v_mul_f32_dpp v15, v241, v15 row_newbcast:5 row_mask:0xf bank_mask:0xf
	s_nop 1
	v_mfma_f32_16x16x32_bf16 v[12:15], v[228:231], v[44:47], v[12:15]
	ds_read_b128 v[228:231], v217 offset:13312
	s_waitcnt lgkmcnt(3)
	v_mul_f32_dpp v16, v240, v16 row_newbcast:6 row_mask:0xf bank_mask:0xf
	v_mul_f32_dpp v17, v241, v17 row_newbcast:6 row_mask:0xf bank_mask:0xf
	v_mul_f32_dpp v18, v240, v18 row_newbcast:7 row_mask:0xf bank_mask:0xf
	v_mul_f32_dpp v19, v241, v19 row_newbcast:7 row_mask:0xf bank_mask:0xf
	s_nop 1
	v_mfma_f32_16x16x32_bf16 v[16:19], v[232:235], v[44:47], v[16:19]
	ds_read_b128 v[232:235], v217 offset:14080
	s_waitcnt lgkmcnt(3)
	v_mul_f32_dpp v20, v240, v20 row_newbcast:8 row_mask:0xf bank_mask:0xf
	v_mul_f32_dpp v21, v241, v21 row_newbcast:8 row_mask:0xf bank_mask:0xf
	v_mul_f32_dpp v22, v240, v22 row_newbcast:9 row_mask:0xf bank_mask:0xf
	v_mul_f32_dpp v23, v241, v23 row_newbcast:9 row_mask:0xf bank_mask:0xf
	s_nop 1
	v_mfma_f32_16x16x32_bf16 v[20:23], v[184:187], v[44:47], v[20:23]
	s_waitcnt lgkmcnt(2)
	v_mul_f32_dpp v24, v240, v24 row_newbcast:10 row_mask:0xf bank_mask:0xf
	v_mul_f32_dpp v25, v241, v25 row_newbcast:10 row_mask:0xf bank_mask:0xf
	v_mul_f32_dpp v26, v240, v26 row_newbcast:11 row_mask:0xf bank_mask:0xf
	v_mul_f32_dpp v27, v241, v27 row_newbcast:11 row_mask:0xf bank_mask:0xf
	s_nop 1
	v_mfma_f32_16x16x32_bf16 v[24:27], v[40:43], v[44:47], v[24:27]
	s_waitcnt lgkmcnt(1)
	v_mul_f32_dpp v28, v240, v28 row_newbcast:12 row_mask:0xf bank_mask:0xf
	v_mul_f32_dpp v29, v241, v29 row_newbcast:12 row_mask:0xf bank_mask:0xf
	v_mul_f32_dpp v30, v240, v30 row_newbcast:13 row_mask:0xf bank_mask:0xf
	v_mul_f32_dpp v31, v241, v31 row_newbcast:13 row_mask:0xf bank_mask:0xf
	s_nop 1
	v_mfma_f32_16x16x32_bf16 v[28:31], v[228:231], v[44:47], v[28:31]
	s_waitcnt lgkmcnt(0)
	v_mul_f32_dpp v32, v240, v32 row_newbcast:14 row_mask:0xf bank_mask:0xf
	v_mul_f32_dpp v33, v241, v33 row_newbcast:14 row_mask:0xf bank_mask:0xf
	v_mul_f32_dpp v34, v240, v34 row_newbcast:15 row_mask:0xf bank_mask:0xf
	v_mul_f32_dpp v35, v241, v35 row_newbcast:15 row_mask:0xf bank_mask:0xf
	s_nop 1
	v_mfma_f32_16x16x32_bf16 v[32:35], v[232:235], v[44:47], v[32:35]
	v_add_u32_e32 v197, s32, v197
	v_add_u32_e32 v198, s32, v198
	v_add_u32_e32 v178, s32, v178
	v_add_u32_e32 v179, s32, v179
	v_lshl_add_u64 v[150:151], v[150:151], 0, v[146:147]
	s_add_i32 s81, s81, 1
	s_add_i32 s62, s62, 16
	s_add_i32 s14, s80, s81
	s_cmp_eq_u32 s14, 2
	s_barrier
	s_cbranch_scc1 .LBB0_1003
	s_branch .LBB0_979
.Lhl_alt_top:
	s_bitcmp1_b32 s81, 0
	s_cselect_b32 s82, 0x5800, 0
	v_lshlrev_b32_e32 v0, 1, v135
	v_lshlrev_b32_e32 v1, 1, v154
	v_add3_u32 v2, s82, v0, v1
	v_add_u32_e32 v207, s82, v63
	v_lshl_add_u32 v227, v54, 1, v207
	v_add_u32_e32 v0, v2, v176
	ds_read_b128 v[36:39], v2 offset:4352
	ds_read_b128 v[40:43], v2
	ds_read_b128 v[208:211], v2 offset:4416
	ds_read_b128 v[184:187], v2 offset:64
	ds_read_b128 v[212:215], v2 offset:4480
	ds_read_b128 v[228:231], v2 offset:128
	ds_read_b128 v[232:235], v2 offset:4544
	ds_read_b128 v[236:239], v2 offset:192
	ds_read_b64 v[188:189], v227 offset:14848
	ds_read2_b64 v[240:243], v0 offset1:4
	ds_read2_b64 v[244:247], v0 offset0:8 offset1:12
	s_and_b64 s[14:15], s[54:55], s[52:53]
	v_mov_b32_e32 v190, v3
	v_mov_b32_e32 v191, v3
	s_waitcnt lgkmcnt(9)
	v_mfma_f32_16x16x32_bf16 v[36:39], v[36:39], v[40:43], 0
	s_waitcnt lgkmcnt(7)
	v_mfma_f32_16x16x32_bf16 v[36:39], v[208:211], v[184:187], v[36:39]
	s_waitcnt lgkmcnt(5)
	v_mfma_f32_16x16x32_bf16 v[36:39], v[212:215], v[228:231], v[36:39]
	s_waitcnt lgkmcnt(3)
	v_mfma_f32_16x16x32_bf16 v[36:39], v[232:235], v[236:239], v[36:39]
	ds_read2_b64 v[208:211], v0 offset0:16 offset1:20
	ds_read2_b64 v[212:215], v0 offset0:24 offset1:28
	v_cvt_pk_bf16_f32 v184, v4, v5
	v_cvt_pk_bf16_f32 v185, v6, v7
	v_cvt_pk_bf16_f32 v186, v8, v9
	v_cvt_pk_bf16_f32 v187, v10, v11
	v_mov_b32_e32 v2, v3
	s_nop 0
	v_cndmask_b32_e64 v192, v38, 0, s[14:15]
	s_and_b64 s[14:15], s[14:15], s[50:51]
	v_cndmask_b32_e64 v0, v37, 0, s[14:15]
	s_and_b64 s[14:15], s[14:15], s[48:49]
	v_cndmask_b32_e64 v36, v36, 0, s[14:15]
	v_cndmask_b32_e64 v1, v39, 0, s[54:55]
	v_cvt_pk_bf16_f32 v0, v36, v0
	v_cvt_pk_bf16_f32 v1, v192, v1
	s_nop 0
	s_waitcnt lgkmcnt(4)
	v_mfma_f32_16x16x32_bf16 v[36:39], v[188:191], v[0:3], 0
	v_cvt_pk_bf16_f32 v40, v12, v13
	v_cvt_pk_bf16_f32 v41, v14, v15
	v_cvt_pk_bf16_f32 v42, v16, v17
	v_cvt_pk_bf16_f32 v43, v18, v19
	v_cvt_pk_bf16_f32 v228, v20, v21
	v_cvt_pk_bf16_f32 v229, v22, v23
	v_cvt_pk_bf16_f32 v230, v24, v25
	v_cvt_pk_bf16_f32 v231, v26, v27
	v_cvt_pk_bf16_f32 v232, v28, v29
	v_cvt_pk_bf16_f32 v233, v30, v31
	v_cvt_pk_bf16_f32 v234, v32, v33
	v_cvt_pk_bf16_f32 v235, v34, v35
	s_waitcnt lgkmcnt(3)
	v_mfma_f32_16x16x32_bf16 v[36:39], v[184:187], v[240:243], v[36:39]
	s_waitcnt lgkmcnt(2)
	v_mfma_f32_16x16x32_bf16 v[36:39], v[40:43], v[244:247], v[36:39]
	s_waitcnt lgkmcnt(1)
	v_mfma_f32_16x16x32_bf16 v[36:39], v[228:231], v[208:211], v[36:39]
	s_waitcnt lgkmcnt(0)
	v_mfma_f32_16x16x32_bf16 v[36:39], v[232:235], v[212:215], v[36:39]
	v_add_u32_e32 v227, v207, v155
	v_add_u32_e32 v216, s82, v142
	v_add3_u32 v217, s82, v155, v156
	v_mov_b32_e32 v44, 0
	v_mov_b32_e32 v45, 0
	v_mov_b32_e32 v46, 0
	v_mov_b32_e32 v47, 0
	s_and_saveexec_b64 s[14:15], s[46:47]
	ds_read_b128 v[44:47], v227 offset:14848
	s_or_b64 exec, exec, s[14:15]
	ds_read_b64 v[240:241], v216 offset:20992
	ds_read_b128 v[184:187], v217 offset:8704
	ds_read_b128 v[40:43], v217 offset:9472
	ds_read_b128 v[228:231], v217 offset:10240
	ds_read_b128 v[232:235], v217 offset:11008
	s_ashr_i32 s14, s32, 4
	s_add_i32 s14, s14, -2
	v_sub_u32_e32 v0, v51, v54
	v_cvt_pk_bf16_f32 v192, v36, v37
	v_cvt_pk_bf16_f32 v193, v38, v39
	v_mad_i32_i24 v0, v0, s14, v197
	global_store_dwordx2 v0, v[192:193], s[100:101]
	s_waitcnt lgkmcnt(3)
	v_mul_f32_dpp v4, v240, v4 row_newbcast:0 row_mask:0xf bank_mask:0xf
	v_mul_f32_dpp v5, v241, v5 row_newbcast:0 row_mask:0xf bank_mask:0xf
	v_mul_f32_dpp v6, v240, v6 row_newbcast:1 row_mask:0xf bank_mask:0xf
	v_mul_f32_dpp v7, v241, v7 row_newbcast:1 row_mask:0xf bank_mask:0xf
	s_nop 1
	v_mfma_f32_16x16x32_bf16 v[4:7], v[184:187], v[44:47], v[4:7]
	ds_read_b128 v[184:187], v217 offset:11776
	s_waitcnt lgkmcnt(3)
	v_mul_f32_dpp v8, v240, v8 row_newbcast:2 row_mask:0xf bank_mask:0xf
	v_mul_f32_dpp v9, v241, v9 row_newbcast:2 row_mask:0xf bank_mask:0xf
	v_mul_f32_dpp v10, v240, v10 row_newbcast:3 row_mask:0xf bank_mask:0xf
	v_mul_f32_dpp v11, v241, v11 row_newbcast:3 row_mask:0xf bank_mask:0xf
	s_nop 1
	v_mfma_f32_16x16x32_bf16 v[8:11], v[40:43], v[44:47], v[8:11]
	ds_read_b128 v[40:43], v217 offset:12544
	s_waitcnt lgkmcnt(3)
	v_mul_f32_dpp v12, v240, v12 row_newbcast:4 row_mask:0xf bank_mask:0xf
	v_mul_f32_dpp v13, v241, v13 row_newbcast:4 row_mask:0xf bank_mask:0xf
	v_mul_f32_dpp v14, v240, v14 row_newbcast:5 row_mask:0xf bank_mask:0xf
	v_mul_f32_dpp v15, v241, v15 row_newbcast:5 row_mask:0xf bank_mask:0xf
	s_nop 1
	v_mfma_f32_16x16x32_bf16 v[12:15], v[228:231], v[44:47], v[12:15]
	ds_read_b128 v[228:231], v217 offset:13312
	s_waitcnt lgkmcnt(3)
	v_mul_f32_dpp v16, v240, v16 row_newbcast:6 row_mask:0xf bank_mask:0xf
	v_mul_f32_dpp v17, v241, v17 row_newbcast:6 row_mask:0xf bank_mask:0xf
	v_mul_f32_dpp v18, v240, v18 row_newbcast:7 row_mask:0xf bank_mask:0xf
	v_mul_f32_dpp v19, v241, v19 row_newbcast:7 row_mask:0xf bank_mask:0xf
	s_nop 1
	v_mfma_f32_16x16x32_bf16 v[16:19], v[232:235], v[44:47], v[16:19]
	ds_read_b128 v[232:235], v217 offset:14080
	s_waitcnt lgkmcnt(3)
	v_mul_f32_dpp v20, v240, v20 row_newbcast:8 row_mask:0xf bank_mask:0xf
	v_mul_f32_dpp v21, v241, v21 row_newbcast:8 row_mask:0xf bank_mask:0xf
	v_mul_f32_dpp v22, v240, v22 row_newbcast:9 row_mask:0xf bank_mask:0xf
	v_mul_f32_dpp v23, v241, v23 row_newbcast:9 row_mask:0xf bank_mask:0xf
	s_nop 1
	v_mfma_f32_16x16x32_bf16 v[20:23], v[184:187], v[44:47], v[20:23]
	s_waitcnt lgkmcnt(2)
	v_mul_f32_dpp v24, v240, v24 row_newbcast:10 row_mask:0xf bank_mask:0xf
	v_mul_f32_dpp v25, v241, v25 row_newbcast:10 row_mask:0xf bank_mask:0xf
	v_mul_f32_dpp v26, v240, v26 row_newbcast:11 row_mask:0xf bank_mask:0xf
	v_mul_f32_dpp v27, v241, v27 row_newbcast:11 row_mask:0xf bank_mask:0xf
	s_nop 1
	v_mfma_f32_16x16x32_bf16 v[24:27], v[40:43], v[44:47], v[24:27]
	s_waitcnt lgkmcnt(1)
	v_mul_f32_dpp v28, v240, v28 row_newbcast:12 row_mask:0xf bank_mask:0xf
	v_mul_f32_dpp v29, v241, v29 row_newbcast:12 row_mask:0xf bank_mask:0xf
	v_mul_f32_dpp v30, v240, v30 row_newbcast:13 row_mask:0xf bank_mask:0xf
	v_mul_f32_dpp v31, v241, v31 row_newbcast:13 row_mask:0xf bank_mask:0xf
	s_nop 1
	v_mfma_f32_16x16x32_bf16 v[28:31], v[228:231], v[44:47], v[28:31]
	s_waitcnt lgkmcnt(0)
	v_mul_f32_dpp v32, v240, v32 row_newbcast:14 row_mask:0xf bank_mask:0xf
	v_mul_f32_dpp v33, v241, v33 row_newbcast:14 row_mask:0xf bank_mask:0xf
	v_mul_f32_dpp v34, v240, v34 row_newbcast:15 row_mask:0xf bank_mask:0xf
	v_mul_f32_dpp v35, v241, v35 row_newbcast:15 row_mask:0xf bank_mask:0xf
	s_nop 1
	v_mfma_f32_16x16x32_bf16 v[32:35], v[232:235], v[44:47], v[32:35]
	s_add_i32 s14, s81, -1
	s_cmp_ge_u32 s14, s61
	s_cbranch_scc1 .Lhl_alt_tail
	s_cmp_ge_u32 s81, s61
	s_waitcnt vmcnt(1)
	v_mov_b32_e32 v199, v157
	v_mov_b32_e32 v200, v159
	v_mov_b32_e32 v201, v161
	v_mov_b32_e32 v202, v163
	v_mov_b32_e32 v203, v166
	v_mov_b32_e32 v204, v167
	v_mov_b32_e32 v205, v168
	v_mov_b32_e32 v206, v169
	v_mov_b64_e32 v[148:149], v[164:165]
	s_cbranch_scc1 .Lhl_alt_982
	global_load_ushort v168, v197, s[12:13]
	global_load_ushort v169, v197, s[98:99]
	global_load_ushort v166, v198, s[12:13]
	global_load_ushort v167, v198, s[98:99]
	global_load_ushort v161, v178, s[12:13]
	global_load_ushort v163, v178, s[98:99]
	global_load_ushort v157, v179, s[12:13]
	global_load_ushort v159, v179, s[98:99]
	global_load_dwordx2 v[164:165], v[150:151], off
